# scan-phase filler: amax butterfly with DPP operands / permlane swaps instead of six ds_bpermute round trips
# speedup vs baseline: 1.0032x; 1.0032x over previous
; DI void phase_scan(int l, int wv, bool fill, bool last) {
;     ...
;             if (filler && c < 32) {
;                 const int it = fidx + 1024 * c, e = it >> 1; unsigned char* dst = (it & 1) ? (unsigned char*)F.V : (unsigned char*)F.U;
;                 float am = 0.f;
; #pragma unroll
;                 for (int c8 = 0; c8 < 8; ++c8) am = fmaxf(am, fmaxf(fmaxf(fabsf(fx[c8].x), fabsf(fx[c8].y)), fmaxf(fabsf(fx[c8].z), fabsf(fx[c8].w))));
; #pragma unroll
;                 for (int o = 1; o < 64; o <<= 1) am = fmaxf(am, __shfl_xor(am, o));
;                 const float inv = am > 0.f ? 7.0f / am : 0.f, sc = am > 0.f ? am * (1.0f / 7.0f) : 0.f;
;                 v32h hx;
; #pragma unroll
;                 for (int c8 = 0; c8 < 8; ++c8) { hx[c8 * 4 + 0] = (_Float16)(fx[c8].x * inv); hx[c8 * 4 + 1] = (_Float16)(fx[c8].y * inv); hx[c8 * 4 + 2] = (_Float16)(fx[c8].z * inv); hx[c8 * 4 + 3] = (_Float16)(fx[c8].w * inv); }
;                 const v6i p = __builtin_amdgcn_cvt_scalef32_pk32_fp6_f16(hx, 1.0f);
;                 eseg_store(dst, e, lane, p);
;                 if (lane == 0) ((float*)(F.ws + WS_ESCALE) + ((it & 1) ? NEXP : 0))[e] = sc;
.LBB0_498:
	s_cmp_lt_u32 s78, 32
	s_cselect_b64 s[62:63], -1, 0
	s_and_b64 s[62:63], s[56:57], s[62:63]
	s_andn2_b64 vcc, exec, s[62:63]
	s_waitcnt lgkmcnt(0)
	s_barrier
	s_cbranch_vccnz .LBB0_503
	v_max_f32_e64 v16, |v35|, |v35|
	v_max_f32_e64 v17, |v34|, |v34|
	v_max_f32_e32 v16, v17, v16
	v_max_f32_e64 v17, |v43|, |v43|
	v_max_f32_e64 v18, |v42|, |v42|
	v_max_f32_e32 v17, v18, v17
	v_max3_f32 v16, |v32|, |v33|, v16
	v_max3_f32 v17, |v40|, |v41|, v17
	v_max3_f32 v16, v16, 0, v17
	v_max_f32_e64 v17, |v55|, |v55|
	v_max_f32_e64 v18, |v54|, |v54|
	v_max_f32_e32 v17, v18, v17
	v_max_f32_e64 v18, |v63|, |v63|
	v_max_f32_e64 v19, |v62|, |v62|
	v_max_f32_e32 v18, v19, v18
	v_max3_f32 v17, |v52|, |v53|, v17
	v_max3_f32 v18, |v60|, |v61|, v18
	v_max3_f32 v16, v16, v17, v18
	v_max_f32_e64 v17, |v51|, |v51|
	v_max_f32_e64 v18, |v50|, |v50|
	v_max_f32_e32 v17, v18, v17
	v_max_f32_e64 v18, |v39|, |v39|
	v_max_f32_e64 v19, |v38|, |v38|
	v_max_f32_e32 v18, v19, v18
	v_max3_f32 v17, |v48|, |v49|, v17
	v_max3_f32 v18, |v36|, |v37|, v18
	v_max3_f32 v16, v16, v17, v18
	v_max_f32_e64 v17, |v47|, |v47|
	v_max_f32_e64 v18, |v46|, |v46|
	v_max_f32_e32 v17, v18, v17
	v_max_f32_e64 v18, |v59|, |v59|
	v_max_f32_e64 v19, |v58|, |v58|
	v_max_f32_e32 v18, v19, v18
	v_max3_f32 v17, |v44|, |v45|, v17
	v_max3_f32 v18, |v56|, |v57|, v18
	v_max3_f32 v16, v16, v17, v18
	s_mov_b32 s64, 0x40e00000
	s_lshl_b32 s81, s78, 10
	s_add_i32 s81, s81, s67
	s_nop 1
	v_max_f32_dpp v16, v16, v16 quad_perm:[1,0,3,2] row_mask:0xf bank_mask:0xf bound_ctrl:1
	s_nop 1
	v_max_f32_dpp v16, v16, v16 quad_perm:[2,3,0,1] row_mask:0xf bank_mask:0xf bound_ctrl:1
	s_nop 1
	v_max_f32_dpp v16, v16, v16 row_half_mirror row_mask:0xf bank_mask:0xf bound_ctrl:1
	s_nop 1
	v_max_f32_dpp v16, v16, v16 row_mirror row_mask:0xf bank_mask:0xf bound_ctrl:1
	v_mov_b32_e32 v17, v16
	s_nop 1
	v_permlane16_swap_b32_e32 v16, v17
	s_nop 1
	v_max_f32_e32 v16, v16, v17
	v_mov_b32_e32 v17, v16
	s_nop 1
	v_permlane32_swap_b32_e32 v16, v17
	s_nop 1
	v_max_f32_e32 v159, v16, v17
	v_div_scale_f32 v16, s[62:63], v159, v159, s64
	v_rcp_f32_e32 v17, v16
	s_ashr_i32 s62, s81, 1
	v_fma_f32 v18, -v16, v17, 1.0
	v_fmac_f32_e32 v17, v18, v17
	v_div_scale_f32 v18, vcc, s64, v159, s64
	v_mul_f32_e32 v19, v18, v17
	v_fma_f32 v20, -v16, v19, v18
	v_fmac_f32_e32 v19, v20, v17
	v_fma_f32 v16, -v16, v19, v18
	v_div_fmas_f32 v16, v16, v17, v19
	v_div_fixup_f32 v16, v16, v159, s64
	v_cmp_lt_f32_e32 vcc, 0, v159
	v_mov_b32_e32 v17, v34
	s_nop 0
	v_cndmask_b32_e32 v208, 0, v16, vcc
	v_mov_b32_e32 v16, v33
	v_pk_mul_f32 v[16:17], v[16:17], v[208:209] op_sel_hi:[1,0]
	v_fma_mixlo_f16 v18, v32, v208, 0
	v_cvt_pk_f16_f32 v17, v16, v17
	v_pack_b32_f16 v16, v18, v17
	v_pk_mov_b32 v[18:19], v[34:35], v[40:41] op_sel:[1,0]
	s_nop 0
	v_pk_mul_f32 v[18:19], v[18:19], v[208:209] op_sel_hi:[1,0]
	s_nop 0
	v_cvt_pk_f16_f32 v20, v18, v19
	v_mov_b32_e32 v18, v41
	v_mov_b32_e32 v19, v42
	v_pk_mul_f32 v[18:19], v[18:19], v[208:209] op_sel_hi:[1,0]
	v_alignbit_b32 v17, v20, v17, 16
	v_cvt_pk_f16_f32 v19, v18, v19
	v_alignbit_b32 v18, v19, v20, 16
	v_pk_mov_b32 v[20:21], v[42:43], v[52:53] op_sel:[1,0]
	s_nop 0
	v_pk_mul_f32 v[20:21], v[20:21], v[208:209] op_sel_hi:[1,0]
	s_nop 0
	v_cvt_pk_f16_f32 v22, v20, v21
	v_mov_b32_e32 v20, v53
	v_mov_b32_e32 v21, v54
	v_pk_mul_f32 v[20:21], v[20:21], v[208:209] op_sel_hi:[1,0]
	v_alignbit_b32 v19, v22, v19, 16
	v_cvt_pk_f16_f32 v21, v20, v21
	v_alignbit_b32 v20, v21, v22, 16
	v_pk_mov_b32 v[22:23], v[54:55], v[60:61] op_sel:[1,0]
	s_nop 0
	v_pk_mul_f32 v[22:23], v[22:23], v[208:209] op_sel_hi:[1,0]
	s_nop 0
	v_cvt_pk_f16_f32 v24, v22, v23
	v_mov_b32_e32 v22, v61
	v_mov_b32_e32 v23, v62
	v_pk_mul_f32 v[22:23], v[22:23], v[208:209] op_sel_hi:[1,0]
	v_alignbit_b32 v21, v24, v21, 16
	v_cvt_pk_f16_f32 v23, v22, v23
	v_alignbit_b32 v22, v23, v24, 16
	v_pk_mov_b32 v[24:25], v[62:63], v[48:49] op_sel:[1,0]
	s_nop 0
	v_pk_mul_f32 v[24:25], v[24:25], v[208:209] op_sel_hi:[1,0]
	s_nop 0
	v_cvt_pk_f16_f32 v26, v24, v25
	v_mov_b32_e32 v24, v49
	v_mov_b32_e32 v25, v50
	v_pk_mul_f32 v[24:25], v[24:25], v[208:209] op_sel_hi:[1,0]
	v_alignbit_b32 v23, v26, v23, 16
	v_cvt_pk_f16_f32 v25, v24, v25
	v_alignbit_b32 v24, v25, v26, 16
	v_pk_mov_b32 v[26:27], v[50:51], v[36:37] op_sel:[1,0]
	s_nop 0
	v_pk_mul_f32 v[26:27], v[26:27], v[208:209] op_sel_hi:[1,0]
	s_nop 0
	v_cvt_pk_f16_f32 v28, v26, v27
	v_mov_b32_e32 v26, v37
	v_mov_b32_e32 v27, v38
	v_pk_mul_f32 v[26:27], v[26:27], v[208:209] op_sel_hi:[1,0]
	v_alignbit_b32 v25, v28, v25, 16
	v_cvt_pk_f16_f32 v27, v26, v27
	v_alignbit_b32 v26, v27, v28, 16
	v_pk_mov_b32 v[28:29], v[38:39], v[44:45] op_sel:[1,0]
	s_nop 0
	v_pk_mul_f32 v[28:29], v[28:29], v[208:209] op_sel_hi:[1,0]
	s_nop 0
	v_cvt_pk_f16_f32 v30, v28, v29
	v_mov_b32_e32 v28, v45
	v_mov_b32_e32 v29, v46
	v_pk_mul_f32 v[28:29], v[28:29], v[208:209] op_sel_hi:[1,0]
	v_alignbit_b32 v27, v30, v27, 16
	v_cvt_pk_f16_f32 v29, v28, v29
	v_alignbit_b32 v28, v29, v30, 16
	v_pk_mov_b32 v[30:31], v[46:47], v[56:57] op_sel:[1,0]
	s_nop 0
	v_pk_mul_f32 v[30:31], v[30:31], v[208:209] op_sel_hi:[1,0]
	s_nop 0
	v_cvt_pk_f16_f32 v161, v30, v31
	v_mov_b32_e32 v30, v57
	v_mov_b32_e32 v31, v58
	v_pk_mul_f32 v[30:31], v[30:31], v[208:209] op_sel_hi:[1,0]
	v_alignbit_b32 v29, v161, v29, 16
	v_cvt_pk_f16_f32 v31, v30, v31
	v_alignbit_b32 v30, v31, v161, 16
	v_lshrrev_b32_e32 v31, 16, v31
	v_fma_mixhi_f16 v31, v59, v208, 0
	v_cvt_scalef32_pk32_fp6_f16 v[232:237], v[16:31], 1.0
	s_lshl_b32 s64, s62, 7
	s_mov_b32 s65, 0
	v_lshl_add_u64 v[16:17], v[122:123], 0, s[64:65]
	global_store_dwordx4 v[16:17], v[232:235], off
	v_and_b32_e32 v18, 7, v239
	s_lshl_b32 s64, s62, 6
	v_lshlrev_b32_e32 v18, 3, v18
	s_sub_u32 s64, 0x200000, s64
	v_mov_b32_e32 v19, 0
	v_sub_u32_e32 v18, s64, v18
	v_lshl_add_u64 v[18:19], v[16:17], 0, v[18:19]
	global_store_dwordx2 v[18:19], v[236:237], off
	s_and_saveexec_b64 s[64:65], s[40:41]
	s_cbranch_execz .LBB0_501
	s_ashr_i32 s63, s62, 31
	s_lshl_b64 s[62:63], s[62:63], 2
	s_add_u32 s62, s70, s62
	v_mul_f32_e32 v16, 0x3e124925, v159
	s_addc_u32 s63, s71, s63
	v_cndmask_b32_e32 v16, 0, v16, vcc
	global_store_dword v129, v16, s[62:63]
